# seam 4-7 a group barrier: attention tasks of a workgroup moved to the two batches of its own group (bg = 4x+2s+i) and RWKV group-norm rows re-dealt to own group rows
# baseline (speedup 1.0000x reference)
.LBB0_2003:
	s_cmp_lt_i32 s86, 5
	s_cselect_b64 s[66:67], -1, 0
	s_and_b64 s[0:1], s[66:67], s[0:1]
	s_andn2_b64 vcc, exec, s[0:1]
	s_cbranch_vccnz .LBB0_2170
	v_writelane_b32 v251, s66, 44
	s_add_u32 s0, s96, 0x2e00000
	v_and_b32_e32 v0, 7, v153
	v_writelane_b32 v251, s67, 45
	v_writelane_b32 v251, s88, 46
	v_lshlrev_b32_e32 v1, 3, v0
	v_and_b32_e32 v99, 15, v153
	v_writelane_b32 v251, s89, 47
	v_writelane_b32 v251, s86, 48
	v_lshrrev_b32_e32 v39, 4, v152
	v_lshrrev_b32_e32 v98, 3, v153
	v_writelane_b32 v251, s87, 49
	v_writelane_b32 v251, s84, 40
	v_writelane_b32 v251, s0, 50
	s_addc_u32 s0, s97, 0
	s_mov_b32 s19, s85
	v_writelane_b32 v251, s0, 51
	s_cmpk_gt_i32 s90, 0x1ff
	s_waitcnt vmcnt(0)
	v_mov_b32_e32 v37, 0
	v_lshlrev_b32_e32 v192, 4, v0
	v_lshlrev_b32_e32 v193, 3, v39
	v_and_b32_e32 v154, 48, v153
	v_lshlrev_b32_e32 v194, 2, v39
	v_mul_u32_u24_e32 v195, 0x90, v99
	v_mul_u32_u24_e32 v196, 0x90, v98
	v_lshlrev_b32_e32 v156, 1, v1
	v_mbcnt_lo_u32_b32 v155, -1, 0
	v_writelane_b32 v251, s90, 43
	s_cbranch_scc1 .LBB0_2011
	v_mov_b32_e32 v157, v37
	v_lshl_add_u64 v[0:1], s[96:97], 0, v[156:157]
	s_mov_b64 s[0:1], 0x2d00000
	v_lshlrev_b32_e32 v36, 4, v99
	v_lshl_add_u64 v[40:41], v[0:1], 0, s[0:1]
	v_lshl_add_u64 v[0:1], s[96:97], 0, v[36:37]
	s_mov_b64 s[0:1], 0x2d80000
	v_lshl_add_u64 v[42:43], v[0:1], 0, s[0:1]
	v_cmp_lt_u32_e64 s[0:1], 31, v152
	v_or_b32_e32 v38, 4, v39
	v_or_b32_e32 v45, 8, v39
	v_writelane_b32 v251, s0, 41
	v_or_b32_e32 v44, 12, v39
	v_or_b32_e32 v2, 0x70, v152
	v_writelane_b32 v251, s1, 42
	v_cmp_lt_u32_e64 s[0:1], 5, v38
	v_or_b32_e32 v47, 16, v39
	v_or_b32_e32 v0, 48, v152
	v_writelane_b32 v251, s0, 52
	v_mul_u32_u24_e32 v5, 0x90, v2
	v_mbcnt_hi_u32_b32 v2, -1, v155
	v_writelane_b32 v251, s1, 53
	v_cmp_lt_u32_e64 s[0:1], 9, v45
	v_mul_u32_u24_e32 v3, 0x90, v0
	v_mul_u32_u24_e32 v8, 0x110, v0
	v_writelane_b32 v251, s0, 54
	v_or_b32_e32 v46, 20, v39
	v_add_u32_e32 v0, 48, v153
	v_writelane_b32 v251, s1, 55
	v_cmp_lt_u32_e64 s[0:1], 13, v44
	v_and_b32_e32 v4, 64, v2
	v_and_or_b32 v0, v0, 63, v4
	v_writelane_b32 v251, s0, 56
	v_lshlrev_b32_e32 v141, 2, v0
	v_or_b32_e32 v0, v4, v99
	v_writelane_b32 v251, s1, 57
	v_cmp_lt_u32_e64 s[0:1], 17, v47
	v_lshlrev_b32_e32 v142, 2, v0
	v_xor_b32_e32 v0, 16, v2
	v_writelane_b32 v251, s0, 58
	v_add_u32_e32 v4, 64, v4
	v_cmp_lt_i32_e32 vcc, v0, v4
	v_writelane_b32 v251, s1, 59
	v_cmp_lt_u32_e64 s[0:1], 21, v46
	v_cndmask_b32_e32 v0, v2, v0, vcc
	v_lshlrev_b32_e32 v146, 2, v0
	v_writelane_b32 v251, s0, 60
	v_xor_b32_e32 v0, 32, v2
	v_cmp_lt_i32_e32 vcc, v0, v4
	v_writelane_b32 v251, s1, 61
	s_movk_i32 s0, 0x100
	v_lshlrev_b32_e64 v134, v39, s0
	s_movk_i32 s0, 0x1000
	v_lshlrev_b32_e64 v135, v39, s0
	s_mov_b32 s0, 0x10000
	v_lshlrev_b32_e64 v136, v39, s0
	s_mov_b32 s0, 0x100000
	v_lshlrev_b32_e64 v137, v39, s0
	s_mov_b32 s0, 0x1000000
	v_add_u32_e32 v6, 0x200, v153
	v_lshlrev_b32_e64 v138, v39, s0
	s_brev_b32 s0, 8
	v_cndmask_b32_e32 v0, v2, v0, vcc
	v_lshrrev_b32_e32 v4, 4, v153
	v_lshrrev_b32_e32 v11, 3, v6
	v_lshrrev_b32_e32 v12, 4, v6
	v_add_u32_e32 v100, 0, v154
	v_add_u32_e32 v1, 0, v193
	v_mul_u32_u24_e32 v7, 0x110, v99
	v_or_b32_e32 v49, 24, v39
	v_or_b32_e32 v48, 28, v39
	v_lshlrev_b32_e64 v139, v39, s0
	v_add_u32_e32 v9, 0, v36
	v_add_u32_e32 v140, 0, v192
	v_lshlrev_b32_e32 v147, 2, v0
	v_lshlrev_b32_e32 v0, 6, v98
	v_lshlrev_b32_e32 v2, 7, v4
	v_mul_u32_u24_e32 v10, 0x110, v4
	v_lshlrev_b32_e32 v4, 6, v11
	v_mul_u32_u24_e32 v11, 0x90, v11
	v_lshlrev_b32_e32 v6, 7, v12
	v_mul_u32_u24_e32 v12, 0x110, v12
	v_readlane_b32 s0, v251, 7
	s_mov_b32 s91, 0
	v_or_b32_e32 v101, 1, v194
	v_or_b32_e32 v102, 2, v194
	v_or_b32_e32 v103, 3, v194
	v_or_b32_e32 v104, 16, v194
	v_or_b32_e32 v105, 17, v194
	v_or_b32_e32 v106, 18, v194
	v_or_b32_e32 v107, 19, v194
	v_or_b32_e32 v108, 32, v194
	v_or_b32_e32 v109, 33, v194
	v_or_b32_e32 v110, 34, v194
	v_or_b32_e32 v111, 35, v194
	v_or_b32_e32 v112, 48, v194
	v_or_b32_e32 v113, 49, v194
	v_or_b32_e32 v114, 50, v194
	v_or_b32_e32 v115, 51, v194
	v_or_b32_e32 v116, 64, v194
	v_or_b32_e32 v117, 0x41, v194
	v_or_b32_e32 v118, 0x42, v194
	v_or_b32_e32 v119, 0x43, v194
	v_or_b32_e32 v120, 0x50, v194
	v_or_b32_e32 v121, 0x51, v194
	v_or_b32_e32 v122, 0x52, v194
	v_or_b32_e32 v123, 0x53, v194
	v_or_b32_e32 v124, 0x60, v194
	v_or_b32_e32 v125, 0x61, v194
	v_or_b32_e32 v126, 0x62, v194
	v_or_b32_e32 v127, 0x63, v194
	v_or_b32_e32 v128, 0x70, v194
	v_or_b32_e32 v129, 0x71, v194
	v_or_b32_e32 v130, 0x72, v194
	v_or_b32_e32 v131, 0x73, v194
	v_cmp_gt_u32_e64 s[2:3], 16, v152
	v_cmp_lt_u32_e64 s[4:5], 15, v152
	v_cmp_eq_u32_e64 s[8:9], 3, v39
	v_cmp_lt_u32_e64 s[20:21], 25, v49
	v_cmp_lt_u32_e64 s[22:23], 29, v48
	v_lshlrev_b32_e64 v132, v39, 1
	v_lshlrev_b32_e64 v133, v39, 16
	v_or_b32_e32 v143, 64, v142
	v_or_b32_e32 v144, 0x80, v142
	v_or_b32_e32 v145, 0xc0, v142
	s_lshl_b32 s7, s0, 4
	v_or_b32_e32 v50, 0x9000040, v193
	v_mov_b32_e32 v51, v37
	v_lshlrev_b32_e32 v52, 1, v0
	v_lshlrev_b32_e32 v54, 1, v2
	v_add_u32_e32 v148, v9, v10
	v_lshlrev_b32_e32 v56, 1, v4
	v_add_u32_e32 v149, v140, v11
	v_lshlrev_b32_e32 v58, 1, v6
	v_add_u32_e32 v150, v9, v12
	s_mov_b32 s6, 0x3e000000
	v_add_u32_e32 v151, v100, v3
	v_add_u32_e32 v157, v100, v5
	v_add_u32_e32 v158, v1, v7
	v_add_u32_e32 v159, v1, v8
	s_mov_b64 s[10:11], 0x80
	v_mov_b32_e32 v160, 0xf149f2ca
	v_mov_b32_e32 v161, 0x461c4000
	v_readlane_b32 s33, v251, 43
	s_and_b32 s0, s33, 7
	s_lshl_b32 s0, s0, 6
	s_bfe_u32 s1, s33, 0x40003
	s_or_b32 s0, s0, s1
	s_lshr_b32 s1, s33, 7
	s_lshl_b32 s1, s1, 5
	s_or_b32 s33, s0, s1
	s_lshl_b32 s95, s33, 3
	s_branch .LBB0_2007
.LBB0_2006:
	s_or_b64 exec, exec, s[0:1]
	s_bitcmp1_b32 s33, 4
	s_cbranch_scc1 .LBB0_2011
	s_and_b32 s0, s33, 15
	s_andn2_b32 s33, s33, 15
	s_sub_i32 s0, 31, s0
	s_add_i32 s33, s33, s0
	s_lshl_b32 s95, s33, 3

.Lnsa_task:
	s_lshr_b32 s65, s26, 8
	s_and_b32 s1, s26, 255
	s_bfe_u32 s28, s1, 0x40003
	s_lshl_b32 s28, s28, 1
	s_lshr_b32 s2, s65, 1
	s_add_i32 s28, s28, s2
	s_sub_i32 s2, 31, s28
	s_bitcmp1_b32 s65, 0
	s_cselect_b32 s28, s2, s28
	s_and_b32 s29, s1, 7
	s_lshl_b32 s29, s29, 2
	s_lshr_b32 s2, s1, 7
	s_lshl_b32 s2, s2, 1
	s_add_i32 s29, s29, s2
	s_and_b32 s2, s65, 1
	s_add_i32 s29, s29, s2
	s_lshr_b32 s30, s29, 1
	s_and_b32 s31, s29, 1
	s_lshl_b32 s36, s31, 2
	s_add_i32 s36, s36, s34
	s_lshl_b32 s33, s28, 6
	s_mov_b32 s32, s28
	s_lshl_b32 s2, s35, 5
	s_add_i32 s2, s2, s33
	v_add_u32_e32 v86, s2, v112
	v_add_u32_e32 v87, 16, v86
	s_lshl_b32 s6, s29, 11
	s_add_i32 s7, s6, s33
	v_add_u32_e32 v221, s7, v152
	v_lshlrev_b32_e32 v221, 2, v221
	s_add_u32 s4, s96, 0x2e00000
	s_addc_u32 s5, s97, 0
	global_load_dword v243, v221, s[4:5]
	s_lshl_b32 s3, s30, 11
	v_add_u32_e32 v220, s3, v86
	v_lshlrev_b32_e32 v234, 10, v220
	s_lshl_b32 s4, s36, 7
	v_add_u32_e32 v234, s4, v234
	v_lshl_add_u32 v234, v113, 4, v234
	v_mov_b32_e32 v235, 0
	s_add_u32 s4, s96, 0xe000000
	s_addc_u32 s5, s97, 0
	v_lshl_add_u64 v[234:235], s[4:5], 0, v[234:235]
	global_load_dwordx4 v[160:163], v[234:235], off
	global_load_dwordx4 v[164:167], v[234:235], off offset:64
	v_lshlrev_b32_e32 v236, 8, v86
	v_lshl_add_u32 v236, v113, 6, v236
	s_add_u32 s4, s96, 0x2c00000
	s_addc_u32 s5, s97, 0
	global_load_dwordx4 v[124:127], v236, s[4:5] offset:0
	global_load_dwordx4 v[128:131], v236, s[4:5] offset:16
	global_load_dwordx4 v[132:135], v236, s[4:5] offset:32
	global_load_dwordx4 v[136:139], v236, s[4:5] offset:48
	s_lshl_b32 s6, s29, 11
	v_add_u32_e32 v221, s6, v86
	v_lshlrev_b32_e32 v221, 2, v221
	s_add_u32 s4, s96, 0x2e00000
	s_addc_u32 s5, s97, 0
	global_load_dword v84, v221, s[4:5]
	v_add_u32_e32 v220, s3, v87
	v_lshlrev_b32_e32 v234, 10, v220
	s_lshl_b32 s4, s36, 7
	v_add_u32_e32 v234, s4, v234
	v_lshl_add_u32 v234, v113, 4, v234
	v_mov_b32_e32 v235, 0
	s_add_u32 s4, s96, 0xe000000
	s_addc_u32 s5, s97, 0
	v_lshl_add_u64 v[234:235], s[4:5], 0, v[234:235]
	global_load_dwordx4 v[168:171], v[234:235], off
	global_load_dwordx4 v[172:175], v[234:235], off offset:64
	v_lshlrev_b32_e32 v236, 8, v87
	v_lshl_add_u32 v236, v113, 6, v236
	s_add_u32 s4, s96, 0x2c00000
	s_addc_u32 s5, s97, 0
	global_load_dwordx4 v[140:143], v236, s[4:5] offset:0
	global_load_dwordx4 v[144:147], v236, s[4:5] offset:16
	global_load_dwordx4 v[148:151], v236, s[4:5] offset:32
	global_load_dwordx4 v[154:157], v236, s[4:5] offset:48
	s_lshl_b32 s6, s29, 11
	v_add_u32_e32 v221, s6, v87
	v_lshlrev_b32_e32 v221, 2, v221
	s_add_u32 s4, s96, 0x2e00000
	s_addc_u32 s5, s97, 0
	global_load_dword v85, v221, s[4:5]
	s_lshl_b32 s3, s30, 11
	s_mul_i32 s2, s36, 6
	s_add_i32 s2, s2, 2
	s_add_u32 s8, s96, 0x13000000
	s_addc_u32 s9, s97, 0
	v_add_u32_e32 v223, s3, v86
	v_lshlrev_b32_e32 v223, 6, v223
	v_add_u32_e32 v223, s2, v223
	global_load_ushort v119, v223, s[8:9]
	global_load_ushort v158, v223, s[8:9] offset:2
	v_add_u32_e32 v223, s3, v87
	v_lshlrev_b32_e32 v223, 6, v223
	v_add_u32_e32 v223, s2, v223
	global_load_ushort v159, v223, s[8:9]
	global_load_ushort v233, v223, s[8:9] offset:2
	s_add_u32 s8, s96, 0x9000000
	s_addc_u32 s9, s97, 0
	v_add_u32_e32 v223, s3, v86
	v_lshlrev_b32_e32 v223, 10, v223
	s_lshl_b32 s2, s36, 7
	v_add_u32_e32 v223, s2, v223
	v_lshl_add_u32 v223, v113, 3, v223
	global_load_dwordx2 v[16:17], v223, s[8:9] offset:0
	global_load_dwordx2 v[20:21], v223, s[8:9] offset:32
	global_load_dwordx2 v[24:25], v223, s[8:9] offset:64
	global_load_dwordx2 v[28:29], v223, s[8:9] offset:96
	v_add_u32_e32 v223, s3, v87
	v_lshlrev_b32_e32 v223, 10, v223
	s_lshl_b32 s2, s36, 7
	v_add_u32_e32 v223, s2, v223
	v_lshl_add_u32 v223, v113, 3, v223
	global_load_dwordx2 v[32:33], v223, s[8:9] offset:0
	global_load_dwordx2 v[36:37], v223, s[8:9] offset:32
	global_load_dwordx2 v[40:41], v223, s[8:9] offset:64
	global_load_dwordx2 v[44:45], v223, s[8:9] offset:96
	s_mul_i32 s2, s30, 0x300000
	s_add_u32 s8, s96, 0x10000000
	s_addc_u32 s9, s97, 0
	s_add_u32 s8, s8, s2
	s_addc_u32 s9, s9, 0
	s_lshl_b32 s2, s31, 7
	s_add_u32 s8, s8, s2
	s_addc_u32 s9, s9, 0
	s_add_u32 s10, s8, 0x200
	s_addc_u32 s11, s9, 0
	global_load_dwordx4 v[88:91], v117, s[10:11]
	s_lshl_b32 s2, s29, 18
	s_add_u32 s10, s96, 0x1b200000
	s_addc_u32 s11, s97, 0
	s_add_u32 s10, s10, s2
	s_addc_u32 s11, s11, 0
	global_load_dwordx4 v[92:95], v118, s[10:11]
	s_add_i32 s12, s32, -8
	s_max_i32 s12, s12, 0
	s_mul_i32 s13, s12, 0x18000
	s_add_u32 s10, s8, 0x400
	s_addc_u32 s11, s9, 0
	s_add_u32 s10, s10, s13
	s_addc_u32 s11, s11, 0
	global_load_dwordx4 v[192:195], v117, s[10:11]
	s_lshl_b32 s13, s12, 7
	s_add_u32 s10, s96, 0x1ba00000
	s_addc_u32 s11, s97, 0
	s_add_u32 s10, s10, s2
	s_addc_u32 s11, s11, 0
	s_add_u32 s10, s10, s13
	s_addc_u32 s11, s11, 0
	global_load_dwordx4 v[196:199], v118, s[10:11]
	s_waitcnt vmcnt(30)
	s_nop 0
	v_or_b32_dpp v243, v243, v243 quad_perm:[1,0,3,2] row_mask:0xf bank_mask:0xf bound_ctrl:1
	s_nop 1
	v_or_b32_dpp v243, v243, v243 quad_perm:[2,3,0,1] row_mask:0xf bank_mask:0xf bound_ctrl:1
	s_nop 1
	v_or_b32_dpp v243, v243, v243 row_ror:4 row_mask:0xf bank_mask:0xf bound_ctrl:1
	s_nop 1
	v_or_b32_dpp v243, v243, v243 row_ror:8 row_mask:0xf bank_mask:0xf bound_ctrl:1
	v_mov_b32_e32 v242, v243
	s_nop 1
	v_permlane16_swap_b32_e32 v243, v242
	v_or_b32_e32 v243, v243, v242
	v_mov_b32_e32 v242, v243
	s_nop 1
	v_permlane32_swap_b32_e32 v243, v242
	v_or_b32_e32 v243, v243, v242
	s_nop 0
	v_readfirstlane_b32 s39, v243
	s_add_u32 s46, s8, 0x200
	s_addc_u32 s47, s9, 0
	s_lshl_b32 s2, s29, 18
	s_add_u32 s48, s96, 0x1b200000
	s_addc_u32 s49, s97, 0
	s_add_u32 s48, s48, s2
	s_addc_u32 s49, s49, 0
	s_lshl_b32 s2, 2, s32
	s_add_i32 s2, s2, -1
	s_and_b32 s38, s39, s2
	s_ff1_i32_b32 s15, s38
	s_add_i32 s65, s38, -1
	s_and_b32 s38, s38, s65
	s_ff1_i32_b32 s41, s38
	s_add_i32 s65, s38, -1
	s_and_b32 s38, s38, s65
	s_ff1_i32_b32 s42, s38
	s_add_i32 s65, s38, -1
	s_and_b32 s38, s38, s65
	s_cmp_eq_u32 s15, 0
	s_cbranch_scc1 .Lnsa_e0_1
	s_mov_b32 s40, s15
	s_max_i32 s65, s40, 0
	s_mul_i32 s56, s65, 0x18000
	s_lshl_b32 s58, s65, 7
	s_add_u32 s56, s46, s56
	s_addc_u32 s57, s47, 0
	s_add_u32 s58, s48, s58
	s_addc_u32 s59, s49, 0
	global_load_dwordx4 v[88:91], v117, s[56:57]
	global_load_dwordx4 v[92:95], v118, s[58:59]

.LBB0_2167:
	v_readlane_b32 s0, v251, 24
	s_cmpk_gt_i32 s88, 0x7fff
	v_readlane_b32 s8, v251, 32
	v_readlane_b32 s9, v251, 33
	v_readlane_b32 s10, v251, 34
	v_readlane_b32 s11, v251, 35
	v_readlane_b32 s12, v251, 36
	v_readlane_b32 s13, v251, 37
	v_readlane_b32 s1, v251, 25
	v_readlane_b32 s2, v251, 26
	v_readlane_b32 s3, v251, 27
	v_readlane_b32 s4, v251, 28
	v_readlane_b32 s5, v251, 29
	v_readlane_b32 s6, v251, 30
	v_readlane_b32 s7, v251, 31
	v_readlane_b32 s14, v251, 38
	v_readlane_b32 s15, v251, 39
	s_cbranch_scc1 .LBB0_2170
	s_mov_b32 s28, s88
	s_mov_b32 s29, s94
	s_and_b32 s30, s90, 7
	s_lshl_b32 s30, s30, 12
	s_lshr_b32 s31, s90, 3
	s_lshl_b32 s31, s31, 3
	s_add_i32 s88, s30, s31
	v_readlane_b32 s31, v251, 7
	s_add_i32 s88, s88, s31
	s_add_i32 s30, s30, 0x1000
	s_movk_i32 s94, 0x100
	v_lshlrev_b32_e32 v0, 5, v152
	v_mov_b32_e32 v1, 0
	v_lshl_add_u64 v[2:3], s[8:9], 0, v[0:1]
	v_lshl_add_u64 v[4:5], s[10:11], 0, v[0:1]
	v_lshl_add_u64 v[6:7], s[12:13], 0, v[0:1]
	v_mbcnt_hi_u32_b32 v0, -1, v155
	v_and_b32_e32 v9, 64, v0
	s_ashr_i32 s89, s88, 31
	v_xor_b32_e32 v8, 1, v0
	v_add_u32_e32 v10, 64, v9
	s_lshl_b64 s[4:5], s[88:89], 10
	v_cmp_lt_i32_e32 vcc, v8, v10
	v_xor_b32_e32 v9, 2, v0
	s_add_u32 s0, s96, s4
	v_cndmask_b32_e32 v8, v0, v8, vcc
	v_cmp_lt_i32_e32 vcc, v9, v10
	v_xor_b32_e32 v11, 4, v0
	s_addc_u32 s1, s97, s5
	s_ashr_i32 s95, s94, 31
	v_cndmask_b32_e32 v9, v0, v9, vcc
	v_cmp_lt_i32_e32 vcc, v11, v10
	s_lshl_b64 s[2:3], s[94:95], 10
	s_add_u32 s4, s74, s4
	v_cndmask_b32_e32 v0, v0, v11, vcc
	v_lshlrev_b32_e32 v8, 2, v8
	v_lshlrev_b32_e32 v9, 2, v9
	v_lshlrev_b32_e32 v10, 2, v0
	v_lshlrev_b32_e32 v0, 4, v152
	s_addc_u32 s5, s75, s5
	s_brev_b32 s6, 32
	s_mov_b32 s7, 0x6000000
	s_mov_b32 s8, 0x1dd00000
	v_mov_b32_e32 v11, 0x3a27c5ac
	s_mov_b32 s9, 0x800000
	s_mov_b32 s10, s88
	global_load_dwordx4 v[56:59], v[2:3], off
	global_load_dwordx4 v[60:63], v[2:3], off offset:16
	global_load_dwordx4 v[64:67], v[4:5], off
	global_load_dwordx4 v[68:71], v[4:5], off offset:16
	global_load_dwordx4 v[72:75], v[6:7], off
	global_load_dwordx4 v[76:79], v[6:7], off offset:16
	s_add_u32 s76, s4, s6
	s_addc_u32 s77, s5, 0
	s_add_u32 s78, s4, s7
	s_addc_u32 s79, s5, 0
	s_add_u32 s80, s0, 0x7000000
	s_addc_u32 s81, s1, 0
	s_add_u32 s82, s0, s8
	s_addc_u32 s83, s1, 0
	s_mov_b32 s32, s10
	global_load_dwordx4 v[80:83], v0, s[4:5]
	global_load_dwordx4 v[84:87], v0, s[80:81]
	global_load_dwordx4 v[88:91], v0, s[76:77]
	global_load_dwordx4 v[92:95], v0, s[78:79]
	global_load_dwordx4 v[96:99], v0, s[82:83]
	v_lshl_add_u64 v[100:101], s[80:81], 0, v[0:1]
	s_add_i32 s32, s32, s94
	s_cmp_lt_i32 s32, s30
	s_cselect_b32 s85, s2, 0
	s_cselect_b32 s91, s3, 0
	s_add_u32 s4, s4, s85
	s_addc_u32 s5, s5, s91
	s_add_u32 s76, s76, s85
	s_addc_u32 s77, s77, s91
	s_add_u32 s78, s78, s85
	s_addc_u32 s79, s79, s91
	s_add_u32 s80, s80, s85
	s_addc_u32 s81, s81, s91
	s_add_u32 s82, s82, s85
	s_addc_u32 s83, s83, s91
	global_load_dwordx4 v[104:107], v0, s[4:5]
	global_load_dwordx4 v[108:111], v0, s[80:81]
	global_load_dwordx4 v[112:115], v0, s[76:77]
	global_load_dwordx4 v[116:119], v0, s[78:79]
	global_load_dwordx4 v[120:123], v0, s[82:83]
	v_lshl_add_u64 v[124:125], s[80:81], 0, v[0:1]
	s_add_i32 s32, s32, s94
	s_cmp_lt_i32 s32, s30
	s_cselect_b32 s85, s2, 0
	s_cselect_b32 s91, s3, 0
	s_add_u32 s4, s4, s85
	s_addc_u32 s5, s5, s91
	s_add_u32 s76, s76, s85
	s_addc_u32 s77, s77, s91
	s_add_u32 s78, s78, s85
	s_addc_u32 s79, s79, s91
	s_add_u32 s80, s80, s85
	s_addc_u32 s81, s81, s91
	s_add_u32 s82, s82, s85
	s_addc_u32 s83, s83, s91
	global_load_dwordx4 v[128:131], v0, s[4:5]
	global_load_dwordx4 v[132:135], v0, s[80:81]
	global_load_dwordx4 v[136:139], v0, s[76:77]
	global_load_dwordx4 v[140:143], v0, s[78:79]
	global_load_dwordx4 v[144:147], v0, s[82:83]
	v_lshl_add_u64 v[148:149], s[80:81], 0, v[0:1]
	s_add_i32 s32, s32, s94
	s_cmp_lt_i32 s32, s30
	s_cselect_b32 s85, s2, 0
	s_cselect_b32 s91, s3, 0
	s_add_u32 s4, s4, s85
	s_addc_u32 s5, s5, s91
	s_add_u32 s76, s76, s85
	s_addc_u32 s77, s77, s91
	s_add_u32 s78, s78, s85
	s_addc_u32 s79, s79, s91
	s_add_u32 s80, s80, s85
	s_addc_u32 s81, s81, s91
	s_add_u32 s82, s82, s85
	s_addc_u32 s83, s83, s91
	s_waitcnt vmcnt(10)
	v_lshlrev_b32_e32 v160, 16, v84
	v_and_b32_e32 v161, 0xffff0000, v84
	v_lshlrev_b32_e32 v162, 16, v85
	v_and_b32_e32 v163, 0xffff0000, v85
	v_lshlrev_b32_e32 v164, 16, v86
	v_and_b32_e32 v165, 0xffff0000, v86
	v_lshlrev_b32_e32 v166, 16, v87
	v_and_b32_e32 v167, 0xffff0000, v87
	v_lshlrev_b32_e32 v168, 16, v80
	v_and_b32_e32 v169, 0xffff0000, v80
	v_lshlrev_b32_e32 v170, 16, v81
	v_and_b32_e32 v171, 0xffff0000, v81
	v_lshlrev_b32_e32 v172, 16, v82
	v_and_b32_e32 v173, 0xffff0000, v82
	v_lshlrev_b32_e32 v174, 16, v83
	v_and_b32_e32 v175, 0xffff0000, v83
	v_lshlrev_b32_e32 v176, 16, v88
	v_and_b32_e32 v177, 0xffff0000, v88
	v_lshlrev_b32_e32 v178, 16, v89
	v_and_b32_e32 v179, 0xffff0000, v89
	v_lshlrev_b32_e32 v180, 16, v90
	v_and_b32_e32 v181, 0xffff0000, v90
	v_lshlrev_b32_e32 v182, 16, v91
	v_and_b32_e32 v183, 0xffff0000, v91
	v_add_f32_e32 v192, 0, v160
	v_pk_mul_f32 v[184:185], v[168:169], v[176:177]
	v_pk_mul_f32 v[186:187], v[170:171], v[178:179]
	v_pk_mul_f32 v[188:189], v[172:173], v[180:181]
	v_pk_mul_f32 v[190:191], v[174:175], v[182:183]
	v_add_f32_e32 v192, v192, v161
	v_pk_mul_f32 v[184:185], v[184:185], v[56:57]
	v_add_f32_e32 v192, v192, v162
	v_pk_mul_f32 v[186:187], v[186:187], v[58:59]
	v_add_f32_e32 v192, v192, v163
	v_pk_mul_f32 v[188:189], v[188:189], v[60:61]
	v_add_f32_e32 v192, v192, v164
	v_pk_mul_f32 v[190:191], v[190:191], v[62:63]
	v_add_f32_e32 v192, v192, v165
	v_add_f32_e32 v192, v192, v166
	v_add_f32_e32 v192, v192, v167
	v_add_f32_e32 v196, 0, v184
	v_add_f32_e32 v196, v185, v196
	v_add_f32_e32 v196, v186, v196
	v_add_f32_e32 v196, v187, v196
	v_add_f32_e32 v196, v188, v196
	v_add_f32_e32 v196, v189, v196
	v_add_f32_e32 v196, v190, v196
	v_add_f32_e32 v196, v191, v196
	v_lshlrev_b32_e32 v168, 16, v92
	v_and_b32_e32 v169, 0xffff0000, v92
	v_add_f32_dpp v192, v192, v192 quad_perm:[1,0,3,2] row_mask:0xf bank_mask:0xf bound_ctrl:1
	v_add_f32_dpp v196, v196, v196 quad_perm:[1,0,3,2] row_mask:0xf bank_mask:0xf bound_ctrl:1
	v_lshlrev_b32_e32 v170, 16, v93
	v_and_b32_e32 v171, 0xffff0000, v93
	v_add_f32_dpp v192, v192, v192 quad_perm:[2,3,0,1] row_mask:0xf bank_mask:0xf bound_ctrl:1
	v_add_f32_dpp v196, v196, v196 quad_perm:[2,3,0,1] row_mask:0xf bank_mask:0xf bound_ctrl:1
	v_lshlrev_b32_e32 v172, 16, v94
	v_and_b32_e32 v173, 0xffff0000, v94
	v_add_f32_dpp v192, v192, v192 row_half_mirror row_mask:0xf bank_mask:0xf bound_ctrl:1
	v_add_f32_dpp v196, v196, v196 row_half_mirror row_mask:0xf bank_mask:0xf bound_ctrl:1
	v_lshlrev_b32_e32 v174, 16, v95
	v_and_b32_e32 v175, 0xffff0000, v95
	v_mul_f32_e32 v194, 0x3c800000, v192
	v_pk_add_f32 v[204:205], v[160:161], v[194:195] op_sel_hi:[1,0] neg_lo:[0,1] neg_hi:[0,1]
	v_pk_add_f32 v[206:207], v[162:163], v[194:195] op_sel_hi:[1,0] neg_lo:[0,1] neg_hi:[0,1]
	v_pk_add_f32 v[208:209], v[164:165], v[194:195] op_sel_hi:[1,0] neg_lo:[0,1] neg_hi:[0,1]
	v_pk_add_f32 v[210:211], v[166:167], v[194:195] op_sel_hi:[1,0] neg_lo:[0,1] neg_hi:[0,1]
	v_pk_mul_f32 v[184:185], v[204:205], v[204:205]
	v_pk_mul_f32 v[186:187], v[206:207], v[206:207]
	v_pk_mul_f32 v[188:189], v[208:209], v[208:209]
	v_pk_mul_f32 v[190:191], v[210:211], v[210:211]
	v_add_f32_e32 v198, v184, v185
	v_add_f32_e32 v198, v186, v198
	v_add_f32_e32 v198, v187, v198
	v_add_f32_e32 v198, v188, v198
	v_add_f32_e32 v198, v189, v198
	v_add_f32_e32 v198, v190, v198
	v_add_f32_e32 v198, v191, v198
	v_lshlrev_b32_e32 v176, 16, v96
	v_and_b32_e32 v177, 0xffff0000, v96
	v_add_f32_dpp v198, v198, v198 quad_perm:[1,0,3,2] row_mask:0xf bank_mask:0xf bound_ctrl:1
	v_lshlrev_b32_e32 v178, 16, v97
	v_and_b32_e32 v179, 0xffff0000, v97
	v_add_f32_dpp v198, v198, v198 quad_perm:[2,3,0,1] row_mask:0xf bank_mask:0xf bound_ctrl:1
	v_lshlrev_b32_e32 v180, 16, v98
	v_and_b32_e32 v181, 0xffff0000, v98
	v_add_f32_dpp v198, v198, v198 row_half_mirror row_mask:0xf bank_mask:0xf bound_ctrl:1
	v_lshlrev_b32_e32 v182, 16, v99
	v_and_b32_e32 v183, 0xffff0000, v99
	v_fmamk_f32 v198, v198, 0x3c800000, v11
	v_mul_f32_e32 v199, 0x4b800000, v198
	v_cmp_gt_f32_e32 vcc, s9, v198
	s_nop 1
	v_cndmask_b32_e32 v198, v198, v199, vcc
	v_rsq_f32_e32 v198, v198
	s_nop 0
	v_mul_f32_e32 v200, 0x45800000, v198
	v_cndmask_b32_e32 v200, v198, v200, vcc
	v_pk_mul_f32 v[204:205], v[204:205], v[200:201] op_sel_hi:[1,0]
	v_pk_mul_f32 v[206:207], v[206:207], v[200:201] op_sel_hi:[1,0]
	v_pk_mul_f32 v[208:209], v[208:209], v[200:201] op_sel_hi:[1,0]
	v_pk_mul_f32 v[210:211], v[210:211], v[200:201] op_sel_hi:[1,0]
	v_pk_fma_f32 v[204:205], v[64:65], v[204:205], v[72:73]
	v_pk_fma_f32 v[206:207], v[66:67], v[206:207], v[74:75]
	v_pk_fma_f32 v[208:209], v[68:69], v[208:209], v[76:77]
	v_pk_fma_f32 v[210:211], v[70:71], v[210:211], v[78:79]
	v_pk_fma_f32 v[204:205], v[196:197], v[168:169], v[204:205] op_sel_hi:[0,1,1]
	v_pk_fma_f32 v[206:207], v[196:197], v[170:171], v[206:207] op_sel_hi:[0,1,1]
	v_pk_fma_f32 v[208:209], v[196:197], v[172:173], v[208:209] op_sel_hi:[0,1,1]
	v_pk_fma_f32 v[210:211], v[196:197], v[174:175], v[210:211] op_sel_hi:[0,1,1]
	v_pk_mul_f32 v[204:205], v[204:205], v[176:177]
	v_pk_mul_f32 v[206:207], v[206:207], v[178:179]
	v_pk_mul_f32 v[208:209], v[208:209], v[180:181]
	v_pk_mul_f32 v[210:211], v[210:211], v[182:183]
	v_cvt_pk_bf16_f32 v212, v204, v205
	v_cvt_pk_bf16_f32 v213, v206, v207
	v_cvt_pk_bf16_f32 v214, v208, v209
	v_cvt_pk_bf16_f32 v215, v210, v211
	global_store_dwordx4 v[100:101], v[212:215], off
	s_add_i32 s10, s10, s94
	s_cmp_lt_i32 s10, s30
	s_cbranch_scc0 .Lrwp_done
.Lrwp_loop:
	global_load_dwordx4 v[80:83], v0, s[4:5]
	global_load_dwordx4 v[84:87], v0, s[80:81]
	global_load_dwordx4 v[88:91], v0, s[76:77]
	global_load_dwordx4 v[92:95], v0, s[78:79]
	global_load_dwordx4 v[96:99], v0, s[82:83]
	v_lshl_add_u64 v[100:101], s[80:81], 0, v[0:1]
	s_add_i32 s32, s32, s94
	s_cmp_lt_i32 s32, s30
	s_cselect_b32 s85, s2, 0
	s_cselect_b32 s91, s3, 0
	s_add_u32 s4, s4, s85
	s_addc_u32 s5, s5, s91
	s_add_u32 s76, s76, s85
	s_addc_u32 s77, s77, s91
	s_add_u32 s78, s78, s85
	s_addc_u32 s79, s79, s91
	s_add_u32 s80, s80, s85
	s_addc_u32 s81, s81, s91
	s_add_u32 s82, s82, s85
	s_addc_u32 s83, s83, s91
	s_waitcnt vmcnt(11)
	v_lshlrev_b32_e32 v160, 16, v108
	v_and_b32_e32 v161, 0xffff0000, v108
	v_lshlrev_b32_e32 v162, 16, v109
	v_and_b32_e32 v163, 0xffff0000, v109
	v_lshlrev_b32_e32 v164, 16, v110
	v_and_b32_e32 v165, 0xffff0000, v110
	v_lshlrev_b32_e32 v166, 16, v111
	v_and_b32_e32 v167, 0xffff0000, v111
	v_lshlrev_b32_e32 v168, 16, v104
	v_and_b32_e32 v169, 0xffff0000, v104
	v_lshlrev_b32_e32 v170, 16, v105
	v_and_b32_e32 v171, 0xffff0000, v105
	v_lshlrev_b32_e32 v172, 16, v106
	v_and_b32_e32 v173, 0xffff0000, v106
	v_lshlrev_b32_e32 v174, 16, v107
	v_and_b32_e32 v175, 0xffff0000, v107
	v_lshlrev_b32_e32 v176, 16, v112
	v_and_b32_e32 v177, 0xffff0000, v112
	v_lshlrev_b32_e32 v178, 16, v113
	v_and_b32_e32 v179, 0xffff0000, v113
	v_lshlrev_b32_e32 v180, 16, v114
	v_and_b32_e32 v181, 0xffff0000, v114
	v_lshlrev_b32_e32 v182, 16, v115
	v_and_b32_e32 v183, 0xffff0000, v115
	v_add_f32_e32 v192, 0, v160
	v_pk_mul_f32 v[184:185], v[168:169], v[176:177]
	v_pk_mul_f32 v[186:187], v[170:171], v[178:179]
	v_pk_mul_f32 v[188:189], v[172:173], v[180:181]
	v_pk_mul_f32 v[190:191], v[174:175], v[182:183]
	v_add_f32_e32 v192, v192, v161
	v_pk_mul_f32 v[184:185], v[184:185], v[56:57]
	v_add_f32_e32 v192, v192, v162
	v_pk_mul_f32 v[186:187], v[186:187], v[58:59]
	v_add_f32_e32 v192, v192, v163
	v_pk_mul_f32 v[188:189], v[188:189], v[60:61]
	v_add_f32_e32 v192, v192, v164
	v_pk_mul_f32 v[190:191], v[190:191], v[62:63]
	v_add_f32_e32 v192, v192, v165
	v_add_f32_e32 v192, v192, v166
	v_add_f32_e32 v192, v192, v167
	v_add_f32_e32 v196, 0, v184
	v_add_f32_e32 v196, v185, v196
	v_add_f32_e32 v196, v186, v196
	v_add_f32_e32 v196, v187, v196
	v_add_f32_e32 v196, v188, v196
	v_add_f32_e32 v196, v189, v196
	v_add_f32_e32 v196, v190, v196
	v_add_f32_e32 v196, v191, v196
	v_lshlrev_b32_e32 v168, 16, v116
	v_and_b32_e32 v169, 0xffff0000, v116
	v_add_f32_dpp v192, v192, v192 quad_perm:[1,0,3,2] row_mask:0xf bank_mask:0xf bound_ctrl:1
	v_add_f32_dpp v196, v196, v196 quad_perm:[1,0,3,2] row_mask:0xf bank_mask:0xf bound_ctrl:1
	v_lshlrev_b32_e32 v170, 16, v117
	v_and_b32_e32 v171, 0xffff0000, v117
	v_add_f32_dpp v192, v192, v192 quad_perm:[2,3,0,1] row_mask:0xf bank_mask:0xf bound_ctrl:1
	v_add_f32_dpp v196, v196, v196 quad_perm:[2,3,0,1] row_mask:0xf bank_mask:0xf bound_ctrl:1
	v_lshlrev_b32_e32 v172, 16, v118
	v_and_b32_e32 v173, 0xffff0000, v118
	v_add_f32_dpp v192, v192, v192 row_half_mirror row_mask:0xf bank_mask:0xf bound_ctrl:1
	v_add_f32_dpp v196, v196, v196 row_half_mirror row_mask:0xf bank_mask:0xf bound_ctrl:1
	v_lshlrev_b32_e32 v174, 16, v119
	v_and_b32_e32 v175, 0xffff0000, v119
	v_mul_f32_e32 v194, 0x3c800000, v192
	v_pk_add_f32 v[204:205], v[160:161], v[194:195] op_sel_hi:[1,0] neg_lo:[0,1] neg_hi:[0,1]
	v_pk_add_f32 v[206:207], v[162:163], v[194:195] op_sel_hi:[1,0] neg_lo:[0,1] neg_hi:[0,1]
	v_pk_add_f32 v[208:209], v[164:165], v[194:195] op_sel_hi:[1,0] neg_lo:[0,1] neg_hi:[0,1]
	v_pk_add_f32 v[210:211], v[166:167], v[194:195] op_sel_hi:[1,0] neg_lo:[0,1] neg_hi:[0,1]
	v_pk_mul_f32 v[184:185], v[204:205], v[204:205]
	v_pk_mul_f32 v[186:187], v[206:207], v[206:207]
	v_pk_mul_f32 v[188:189], v[208:209], v[208:209]
	v_pk_mul_f32 v[190:191], v[210:211], v[210:211]
	v_add_f32_e32 v198, v184, v185
	v_add_f32_e32 v198, v186, v198
	v_add_f32_e32 v198, v187, v198
	v_add_f32_e32 v198, v188, v198
	v_add_f32_e32 v198, v189, v198
	v_add_f32_e32 v198, v190, v198
	v_add_f32_e32 v198, v191, v198
	v_lshlrev_b32_e32 v176, 16, v120
	v_and_b32_e32 v177, 0xffff0000, v120
	v_add_f32_dpp v198, v198, v198 quad_perm:[1,0,3,2] row_mask:0xf bank_mask:0xf bound_ctrl:1
	v_lshlrev_b32_e32 v178, 16, v121
	v_and_b32_e32 v179, 0xffff0000, v121
	v_add_f32_dpp v198, v198, v198 quad_perm:[2,3,0,1] row_mask:0xf bank_mask:0xf bound_ctrl:1
	v_lshlrev_b32_e32 v180, 16, v122
	v_and_b32_e32 v181, 0xffff0000, v122
	v_add_f32_dpp v198, v198, v198 row_half_mirror row_mask:0xf bank_mask:0xf bound_ctrl:1
	v_lshlrev_b32_e32 v182, 16, v123
	v_and_b32_e32 v183, 0xffff0000, v123
	v_fmamk_f32 v198, v198, 0x3c800000, v11
	v_mul_f32_e32 v199, 0x4b800000, v198
	v_cmp_gt_f32_e32 vcc, s9, v198
	s_nop 1
	v_cndmask_b32_e32 v198, v198, v199, vcc
	v_rsq_f32_e32 v198, v198
	s_nop 0
	v_mul_f32_e32 v200, 0x45800000, v198
	v_cndmask_b32_e32 v200, v198, v200, vcc
	v_pk_mul_f32 v[204:205], v[204:205], v[200:201] op_sel_hi:[1,0]
	v_pk_mul_f32 v[206:207], v[206:207], v[200:201] op_sel_hi:[1,0]
	v_pk_mul_f32 v[208:209], v[208:209], v[200:201] op_sel_hi:[1,0]
	v_pk_mul_f32 v[210:211], v[210:211], v[200:201] op_sel_hi:[1,0]
	v_pk_fma_f32 v[204:205], v[64:65], v[204:205], v[72:73]
	v_pk_fma_f32 v[206:207], v[66:67], v[206:207], v[74:75]
	v_pk_fma_f32 v[208:209], v[68:69], v[208:209], v[76:77]
	v_pk_fma_f32 v[210:211], v[70:71], v[210:211], v[78:79]
	v_pk_fma_f32 v[204:205], v[196:197], v[168:169], v[204:205] op_sel_hi:[0,1,1]
	v_pk_fma_f32 v[206:207], v[196:197], v[170:171], v[206:207] op_sel_hi:[0,1,1]
	v_pk_fma_f32 v[208:209], v[196:197], v[172:173], v[208:209] op_sel_hi:[0,1,1]
	v_pk_fma_f32 v[210:211], v[196:197], v[174:175], v[210:211] op_sel_hi:[0,1,1]
	v_pk_mul_f32 v[204:205], v[204:205], v[176:177]
	v_pk_mul_f32 v[206:207], v[206:207], v[178:179]
	v_pk_mul_f32 v[208:209], v[208:209], v[180:181]
	v_pk_mul_f32 v[210:211], v[210:211], v[182:183]
	v_cvt_pk_bf16_f32 v212, v204, v205
	v_cvt_pk_bf16_f32 v213, v206, v207
	v_cvt_pk_bf16_f32 v214, v208, v209
	v_cvt_pk_bf16_f32 v215, v210, v211
	global_store_dwordx4 v[124:125], v[212:215], off
	s_add_i32 s10, s10, s94
	s_cmp_lt_i32 s10, s30
	s_cbranch_scc0 .Lrwp_done
	global_load_dwordx4 v[104:107], v0, s[4:5]
	global_load_dwordx4 v[108:111], v0, s[80:81]
	global_load_dwordx4 v[112:115], v0, s[76:77]
	global_load_dwordx4 v[116:119], v0, s[78:79]
	global_load_dwordx4 v[120:123], v0, s[82:83]
	v_lshl_add_u64 v[124:125], s[80:81], 0, v[0:1]
	s_add_i32 s32, s32, s94
	s_cmp_lt_i32 s32, s30
	s_cselect_b32 s85, s2, 0
	s_cselect_b32 s91, s3, 0
	s_add_u32 s4, s4, s85
	s_addc_u32 s5, s5, s91
	s_add_u32 s76, s76, s85
	s_addc_u32 s77, s77, s91
	s_add_u32 s78, s78, s85
	s_addc_u32 s79, s79, s91
	s_add_u32 s80, s80, s85
	s_addc_u32 s81, s81, s91
	s_add_u32 s82, s82, s85
	s_addc_u32 s83, s83, s91
	s_waitcnt vmcnt(11)
	v_lshlrev_b32_e32 v160, 16, v132
	v_and_b32_e32 v161, 0xffff0000, v132
	v_lshlrev_b32_e32 v162, 16, v133
	v_and_b32_e32 v163, 0xffff0000, v133
	v_lshlrev_b32_e32 v164, 16, v134
	v_and_b32_e32 v165, 0xffff0000, v134
	v_lshlrev_b32_e32 v166, 16, v135
	v_and_b32_e32 v167, 0xffff0000, v135
	v_lshlrev_b32_e32 v168, 16, v128
	v_and_b32_e32 v169, 0xffff0000, v128
	v_lshlrev_b32_e32 v170, 16, v129
	v_and_b32_e32 v171, 0xffff0000, v129
	v_lshlrev_b32_e32 v172, 16, v130
	v_and_b32_e32 v173, 0xffff0000, v130
	v_lshlrev_b32_e32 v174, 16, v131
	v_and_b32_e32 v175, 0xffff0000, v131
	v_lshlrev_b32_e32 v176, 16, v136
	v_and_b32_e32 v177, 0xffff0000, v136
	v_lshlrev_b32_e32 v178, 16, v137
	v_and_b32_e32 v179, 0xffff0000, v137
	v_lshlrev_b32_e32 v180, 16, v138
	v_and_b32_e32 v181, 0xffff0000, v138
	v_lshlrev_b32_e32 v182, 16, v139
	v_and_b32_e32 v183, 0xffff0000, v139
	v_add_f32_e32 v192, 0, v160
	v_pk_mul_f32 v[184:185], v[168:169], v[176:177]
	v_pk_mul_f32 v[186:187], v[170:171], v[178:179]
	v_pk_mul_f32 v[188:189], v[172:173], v[180:181]
	v_pk_mul_f32 v[190:191], v[174:175], v[182:183]
	v_add_f32_e32 v192, v192, v161
	v_pk_mul_f32 v[184:185], v[184:185], v[56:57]
	v_add_f32_e32 v192, v192, v162
	v_pk_mul_f32 v[186:187], v[186:187], v[58:59]
	v_add_f32_e32 v192, v192, v163
	v_pk_mul_f32 v[188:189], v[188:189], v[60:61]
	v_add_f32_e32 v192, v192, v164
	v_pk_mul_f32 v[190:191], v[190:191], v[62:63]
	v_add_f32_e32 v192, v192, v165
	v_add_f32_e32 v192, v192, v166
	v_add_f32_e32 v192, v192, v167
	v_add_f32_e32 v196, 0, v184
	v_add_f32_e32 v196, v185, v196
	v_add_f32_e32 v196, v186, v196
	v_add_f32_e32 v196, v187, v196
	v_add_f32_e32 v196, v188, v196
	v_add_f32_e32 v196, v189, v196
	v_add_f32_e32 v196, v190, v196
	v_add_f32_e32 v196, v191, v196
	v_lshlrev_b32_e32 v168, 16, v140
	v_and_b32_e32 v169, 0xffff0000, v140
	v_add_f32_dpp v192, v192, v192 quad_perm:[1,0,3,2] row_mask:0xf bank_mask:0xf bound_ctrl:1
	v_add_f32_dpp v196, v196, v196 quad_perm:[1,0,3,2] row_mask:0xf bank_mask:0xf bound_ctrl:1
	v_lshlrev_b32_e32 v170, 16, v141
	v_and_b32_e32 v171, 0xffff0000, v141
	v_add_f32_dpp v192, v192, v192 quad_perm:[2,3,0,1] row_mask:0xf bank_mask:0xf bound_ctrl:1
	v_add_f32_dpp v196, v196, v196 quad_perm:[2,3,0,1] row_mask:0xf bank_mask:0xf bound_ctrl:1
	v_lshlrev_b32_e32 v172, 16, v142
	v_and_b32_e32 v173, 0xffff0000, v142
	v_add_f32_dpp v192, v192, v192 row_half_mirror row_mask:0xf bank_mask:0xf bound_ctrl:1
	v_add_f32_dpp v196, v196, v196 row_half_mirror row_mask:0xf bank_mask:0xf bound_ctrl:1
	v_lshlrev_b32_e32 v174, 16, v143
	v_and_b32_e32 v175, 0xffff0000, v143
	v_mul_f32_e32 v194, 0x3c800000, v192
	v_pk_add_f32 v[204:205], v[160:161], v[194:195] op_sel_hi:[1,0] neg_lo:[0,1] neg_hi:[0,1]
	v_pk_add_f32 v[206:207], v[162:163], v[194:195] op_sel_hi:[1,0] neg_lo:[0,1] neg_hi:[0,1]
	v_pk_add_f32 v[208:209], v[164:165], v[194:195] op_sel_hi:[1,0] neg_lo:[0,1] neg_hi:[0,1]
	v_pk_add_f32 v[210:211], v[166:167], v[194:195] op_sel_hi:[1,0] neg_lo:[0,1] neg_hi:[0,1]
	v_pk_mul_f32 v[184:185], v[204:205], v[204:205]
	v_pk_mul_f32 v[186:187], v[206:207], v[206:207]
	v_pk_mul_f32 v[188:189], v[208:209], v[208:209]
	v_pk_mul_f32 v[190:191], v[210:211], v[210:211]
	v_add_f32_e32 v198, v184, v185
	v_add_f32_e32 v198, v186, v198
	v_add_f32_e32 v198, v187, v198
	v_add_f32_e32 v198, v188, v198
	v_add_f32_e32 v198, v189, v198
	v_add_f32_e32 v198, v190, v198
	v_add_f32_e32 v198, v191, v198
	v_lshlrev_b32_e32 v176, 16, v144
	v_and_b32_e32 v177, 0xffff0000, v144
	v_add_f32_dpp v198, v198, v198 quad_perm:[1,0,3,2] row_mask:0xf bank_mask:0xf bound_ctrl:1
	v_lshlrev_b32_e32 v178, 16, v145
	v_and_b32_e32 v179, 0xffff0000, v145
	v_add_f32_dpp v198, v198, v198 quad_perm:[2,3,0,1] row_mask:0xf bank_mask:0xf bound_ctrl:1
	v_lshlrev_b32_e32 v180, 16, v146
	v_and_b32_e32 v181, 0xffff0000, v146
	v_add_f32_dpp v198, v198, v198 row_half_mirror row_mask:0xf bank_mask:0xf bound_ctrl:1
	v_lshlrev_b32_e32 v182, 16, v147
	v_and_b32_e32 v183, 0xffff0000, v147
	v_fmamk_f32 v198, v198, 0x3c800000, v11
	v_mul_f32_e32 v199, 0x4b800000, v198
	v_cmp_gt_f32_e32 vcc, s9, v198
	s_nop 1
	v_cndmask_b32_e32 v198, v198, v199, vcc
	v_rsq_f32_e32 v198, v198
	s_nop 0
	v_mul_f32_e32 v200, 0x45800000, v198
	v_cndmask_b32_e32 v200, v198, v200, vcc
	v_pk_mul_f32 v[204:205], v[204:205], v[200:201] op_sel_hi:[1,0]
	v_pk_mul_f32 v[206:207], v[206:207], v[200:201] op_sel_hi:[1,0]
	v_pk_mul_f32 v[208:209], v[208:209], v[200:201] op_sel_hi:[1,0]
	v_pk_mul_f32 v[210:211], v[210:211], v[200:201] op_sel_hi:[1,0]
	v_pk_fma_f32 v[204:205], v[64:65], v[204:205], v[72:73]
	v_pk_fma_f32 v[206:207], v[66:67], v[206:207], v[74:75]
	v_pk_fma_f32 v[208:209], v[68:69], v[208:209], v[76:77]
	v_pk_fma_f32 v[210:211], v[70:71], v[210:211], v[78:79]
	v_pk_fma_f32 v[204:205], v[196:197], v[168:169], v[204:205] op_sel_hi:[0,1,1]
	v_pk_fma_f32 v[206:207], v[196:197], v[170:171], v[206:207] op_sel_hi:[0,1,1]
	v_pk_fma_f32 v[208:209], v[196:197], v[172:173], v[208:209] op_sel_hi:[0,1,1]
	v_pk_fma_f32 v[210:211], v[196:197], v[174:175], v[210:211] op_sel_hi:[0,1,1]
	v_pk_mul_f32 v[204:205], v[204:205], v[176:177]
	v_pk_mul_f32 v[206:207], v[206:207], v[178:179]
	v_pk_mul_f32 v[208:209], v[208:209], v[180:181]
	v_pk_mul_f32 v[210:211], v[210:211], v[182:183]
	v_cvt_pk_bf16_f32 v212, v204, v205
	v_cvt_pk_bf16_f32 v213, v206, v207
	v_cvt_pk_bf16_f32 v214, v208, v209
	v_cvt_pk_bf16_f32 v215, v210, v211
	global_store_dwordx4 v[148:149], v[212:215], off
	s_add_i32 s10, s10, s94
	s_cmp_lt_i32 s10, s30
	s_cbranch_scc0 .Lrwp_done
	global_load_dwordx4 v[128:131], v0, s[4:5]
	global_load_dwordx4 v[132:135], v0, s[80:81]
	global_load_dwordx4 v[136:139], v0, s[76:77]
	global_load_dwordx4 v[140:143], v0, s[78:79]
	global_load_dwordx4 v[144:147], v0, s[82:83]
	v_lshl_add_u64 v[148:149], s[80:81], 0, v[0:1]
	s_add_i32 s32, s32, s94
	s_cmp_lt_i32 s32, s30
	s_cselect_b32 s85, s2, 0
	s_cselect_b32 s91, s3, 0
	s_add_u32 s4, s4, s85
	s_addc_u32 s5, s5, s91
	s_add_u32 s76, s76, s85
	s_addc_u32 s77, s77, s91
	s_add_u32 s78, s78, s85
	s_addc_u32 s79, s79, s91
	s_add_u32 s80, s80, s85
	s_addc_u32 s81, s81, s91
	s_add_u32 s82, s82, s85
	s_addc_u32 s83, s83, s91
	s_waitcnt vmcnt(11)
	v_lshlrev_b32_e32 v160, 16, v84
	v_and_b32_e32 v161, 0xffff0000, v84
	v_lshlrev_b32_e32 v162, 16, v85
	v_and_b32_e32 v163, 0xffff0000, v85
	v_lshlrev_b32_e32 v164, 16, v86
	v_and_b32_e32 v165, 0xffff0000, v86
	v_lshlrev_b32_e32 v166, 16, v87
	v_and_b32_e32 v167, 0xffff0000, v87
	v_lshlrev_b32_e32 v168, 16, v80
	v_and_b32_e32 v169, 0xffff0000, v80
	v_lshlrev_b32_e32 v170, 16, v81
	v_and_b32_e32 v171, 0xffff0000, v81
	v_lshlrev_b32_e32 v172, 16, v82
	v_and_b32_e32 v173, 0xffff0000, v82
	v_lshlrev_b32_e32 v174, 16, v83
	v_and_b32_e32 v175, 0xffff0000, v83
	v_lshlrev_b32_e32 v176, 16, v88
	v_and_b32_e32 v177, 0xffff0000, v88
	v_lshlrev_b32_e32 v178, 16, v89
	v_and_b32_e32 v179, 0xffff0000, v89
	v_lshlrev_b32_e32 v180, 16, v90
	v_and_b32_e32 v181, 0xffff0000, v90
	v_lshlrev_b32_e32 v182, 16, v91
	v_and_b32_e32 v183, 0xffff0000, v91
	v_add_f32_e32 v192, 0, v160
	v_pk_mul_f32 v[184:185], v[168:169], v[176:177]
	v_pk_mul_f32 v[186:187], v[170:171], v[178:179]
	v_pk_mul_f32 v[188:189], v[172:173], v[180:181]
	v_pk_mul_f32 v[190:191], v[174:175], v[182:183]
	v_add_f32_e32 v192, v192, v161
	v_pk_mul_f32 v[184:185], v[184:185], v[56:57]
	v_add_f32_e32 v192, v192, v162
	v_pk_mul_f32 v[186:187], v[186:187], v[58:59]
	v_add_f32_e32 v192, v192, v163
	v_pk_mul_f32 v[188:189], v[188:189], v[60:61]
	v_add_f32_e32 v192, v192, v164
	v_pk_mul_f32 v[190:191], v[190:191], v[62:63]
	v_add_f32_e32 v192, v192, v165
	v_add_f32_e32 v192, v192, v166
	v_add_f32_e32 v192, v192, v167
	v_add_f32_e32 v196, 0, v184
	v_add_f32_e32 v196, v185, v196
	v_add_f32_e32 v196, v186, v196
	v_add_f32_e32 v196, v187, v196
	v_add_f32_e32 v196, v188, v196
	v_add_f32_e32 v196, v189, v196
	v_add_f32_e32 v196, v190, v196
	v_add_f32_e32 v196, v191, v196
	v_lshlrev_b32_e32 v168, 16, v92
	v_and_b32_e32 v169, 0xffff0000, v92
	v_add_f32_dpp v192, v192, v192 quad_perm:[1,0,3,2] row_mask:0xf bank_mask:0xf bound_ctrl:1
	v_add_f32_dpp v196, v196, v196 quad_perm:[1,0,3,2] row_mask:0xf bank_mask:0xf bound_ctrl:1
	v_lshlrev_b32_e32 v170, 16, v93
	v_and_b32_e32 v171, 0xffff0000, v93
	v_add_f32_dpp v192, v192, v192 quad_perm:[2,3,0,1] row_mask:0xf bank_mask:0xf bound_ctrl:1
	v_add_f32_dpp v196, v196, v196 quad_perm:[2,3,0,1] row_mask:0xf bank_mask:0xf bound_ctrl:1
	v_lshlrev_b32_e32 v172, 16, v94
	v_and_b32_e32 v173, 0xffff0000, v94
	v_add_f32_dpp v192, v192, v192 row_half_mirror row_mask:0xf bank_mask:0xf bound_ctrl:1
	v_add_f32_dpp v196, v196, v196 row_half_mirror row_mask:0xf bank_mask:0xf bound_ctrl:1
	v_lshlrev_b32_e32 v174, 16, v95
	v_and_b32_e32 v175, 0xffff0000, v95
	v_mul_f32_e32 v194, 0x3c800000, v192
	v_pk_add_f32 v[204:205], v[160:161], v[194:195] op_sel_hi:[1,0] neg_lo:[0,1] neg_hi:[0,1]
	v_pk_add_f32 v[206:207], v[162:163], v[194:195] op_sel_hi:[1,0] neg_lo:[0,1] neg_hi:[0,1]
	v_pk_add_f32 v[208:209], v[164:165], v[194:195] op_sel_hi:[1,0] neg_lo:[0,1] neg_hi:[0,1]
	v_pk_add_f32 v[210:211], v[166:167], v[194:195] op_sel_hi:[1,0] neg_lo:[0,1] neg_hi:[0,1]
	v_pk_mul_f32 v[184:185], v[204:205], v[204:205]
	v_pk_mul_f32 v[186:187], v[206:207], v[206:207]
	v_pk_mul_f32 v[188:189], v[208:209], v[208:209]
	v_pk_mul_f32 v[190:191], v[210:211], v[210:211]
	v_add_f32_e32 v198, v184, v185
	v_add_f32_e32 v198, v186, v198
	v_add_f32_e32 v198, v187, v198
	v_add_f32_e32 v198, v188, v198
	v_add_f32_e32 v198, v189, v198
	v_add_f32_e32 v198, v190, v198
	v_add_f32_e32 v198, v191, v198
	v_lshlrev_b32_e32 v176, 16, v96
	v_and_b32_e32 v177, 0xffff0000, v96
	v_add_f32_dpp v198, v198, v198 quad_perm:[1,0,3,2] row_mask:0xf bank_mask:0xf bound_ctrl:1
	v_lshlrev_b32_e32 v178, 16, v97
	v_and_b32_e32 v179, 0xffff0000, v97
	v_add_f32_dpp v198, v198, v198 quad_perm:[2,3,0,1] row_mask:0xf bank_mask:0xf bound_ctrl:1
	v_lshlrev_b32_e32 v180, 16, v98
	v_and_b32_e32 v181, 0xffff0000, v98
	v_add_f32_dpp v198, v198, v198 row_half_mirror row_mask:0xf bank_mask:0xf bound_ctrl:1
	v_lshlrev_b32_e32 v182, 16, v99
	v_and_b32_e32 v183, 0xffff0000, v99
	v_fmamk_f32 v198, v198, 0x3c800000, v11
	v_mul_f32_e32 v199, 0x4b800000, v198
	v_cmp_gt_f32_e32 vcc, s9, v198
	s_nop 1
	v_cndmask_b32_e32 v198, v198, v199, vcc
	v_rsq_f32_e32 v198, v198
	s_nop 0
	v_mul_f32_e32 v200, 0x45800000, v198
	v_cndmask_b32_e32 v200, v198, v200, vcc
	v_pk_mul_f32 v[204:205], v[204:205], v[200:201] op_sel_hi:[1,0]
	v_pk_mul_f32 v[206:207], v[206:207], v[200:201] op_sel_hi:[1,0]
	v_pk_mul_f32 v[208:209], v[208:209], v[200:201] op_sel_hi:[1,0]
	v_pk_mul_f32 v[210:211], v[210:211], v[200:201] op_sel_hi:[1,0]
	v_pk_fma_f32 v[204:205], v[64:65], v[204:205], v[72:73]
	v_pk_fma_f32 v[206:207], v[66:67], v[206:207], v[74:75]
	v_pk_fma_f32 v[208:209], v[68:69], v[208:209], v[76:77]
	v_pk_fma_f32 v[210:211], v[70:71], v[210:211], v[78:79]
	v_pk_fma_f32 v[204:205], v[196:197], v[168:169], v[204:205] op_sel_hi:[0,1,1]
	v_pk_fma_f32 v[206:207], v[196:197], v[170:171], v[206:207] op_sel_hi:[0,1,1]
	v_pk_fma_f32 v[208:209], v[196:197], v[172:173], v[208:209] op_sel_hi:[0,1,1]
	v_pk_fma_f32 v[210:211], v[196:197], v[174:175], v[210:211] op_sel_hi:[0,1,1]
	v_pk_mul_f32 v[204:205], v[204:205], v[176:177]
	v_pk_mul_f32 v[206:207], v[206:207], v[178:179]
	v_pk_mul_f32 v[208:209], v[208:209], v[180:181]
	v_pk_mul_f32 v[210:211], v[210:211], v[182:183]
	v_cvt_pk_bf16_f32 v212, v204, v205
	v_cvt_pk_bf16_f32 v213, v206, v207
	v_cvt_pk_bf16_f32 v214, v208, v209
	v_cvt_pk_bf16_f32 v215, v210, v211
	global_store_dwordx4 v[100:101], v[212:215], off
	s_add_i32 s10, s10, s94
	s_cmp_lt_i32 s10, s30
	s_cbranch_scc1 .Lrwp_loop
.Lrwp_done:
	s_mov_b32 s88, s28
	s_mov_b32 s94, s29
	s_waitcnt vmcnt(0)
.LBB0_2170:
	s_cmp_lt_i32 s87, 6
	s_cselect_b64 s[0:1], -1, 0
	s_xor_b64 s[2:3], s[66:67], -1
	s_or_b64 s[0:1], s[2:3], s[0:1]
	s_and_b64 vcc, exec, s[0:1]
	s_cbranch_vccnz .LBB0_2224
	s_waitcnt vmcnt(0)
	s_waitcnt vmcnt(0)
	s_barrier
	s_mov_b64 s[0:1], exec
	v_readlane_b32 s2, v251, 1
	v_readlane_b32 s3, v251, 2
	s_and_b64 s[2:3], s[0:1], s[2:3]
	s_mov_b64 exec, s[2:3]
	s_cbranch_execz .LBB0_2223
	s_waitcnt vmcnt(0) expcnt(0) lgkmcnt(0)
	buffer_inv sc1
	s_and_b32 s2, s90, 7
	s_lshl_b32 s2, s2, 8
	s_add_i32 s2, s2, 0x3600
	v_mov_b32_e32 v0, s2
	v_mov_b32_e32 v2, 1
	global_atomic_add v0, v0, v2, s[96:97] sc0
	s_nop 0
	v_mov_b32_e32 v2, 0x3e00
	global_load_dword v2, v2, s[96:97] sc1
	s_waitcnt vmcnt(0)
	v_readfirstlane_b32 s3, v2
	v_readfirstlane_b32 vcc_lo, v0
	s_cmp_lg_u32 s3, 0
	s_cbranch_scc1 .Lgb_orig4
	s_or_b32 s3, vcc_lo, 31
	s_cmp_eq_u32 s3, vcc_lo
	s_cbranch_scc1 .Lgb_done4
	s_add_i32 s3, s3, 1
	s_mov_b32 vcc_hi, 0
	v_mov_b32_e32 v0, s2
